# grid barrier: non-leader workgroups poll the top generation word directly
# baseline (speedup 1.0000x reference)
; __device__ __forceinline__ unsigned xb_ld(unsigned* p)              { return __hip_atomic_load(p, __ATOMIC_RELAXED, __HIP_MEMORY_SCOPE_AGENT); }
; __device__ __forceinline__ unsigned xb_add(unsigned* p, unsigned v) { return __hip_atomic_fetch_add(p, v, __ATOMIC_RELAXED, __HIP_MEMORY_SCOPE_AGENT); }
; #define XB_SPIN(cond, bar) do { unsigned _sp = 0; while (cond) { __builtin_amdgcn_s_sleep(1); \
;     if ((++_sp & 255u) == 0u) { if (xb_ld(&(bar)[XB_TMO])) break; if (_sp > XB_SPIN_CAP) { atomicAdd(&(bar)[XB_TMO], 1u); break; } } } } while (0)
; __device__ __forceinline__ void xcd_barrier(const XcdBarrier& b) {
;     ...
;         unsigned nloc = b.st[0], nx = b.st[1];
;         if (nloc == 0u) { xcd_barrier_complete(bar, b.x, nloc, nx); b.st[0] = nloc; b.st[1] = nx; }
;         const unsigned old = xb_add(&bar[XB_XSUB(b.x)], 1u);
;         const unsigned gen = old / nloc;
;         if (old + 1u == (gen + 1u) * nloc) {
;             __builtin_amdgcn_fence(__ATOMIC_RELEASE, "agent");
;             asm volatile("s_waitcnt vmcnt(0)" ::: "memory");
;             const unsigned og = xb_add(&bar[XB_TOP], 1u);
;             const unsigned tg = og / nx;
;             if (og + 1u == (tg + 1u) * nx) xb_add(&bar[XB_TOPGEN], 1u);
;             else XB_SPIN(xb_ld(&bar[XB_TOPGEN]) == tg, bar);
;             __builtin_amdgcn_fence(__ATOMIC_ACQUIRE, "agent");
;             xb_add(&bar[XB_XGEN(b.x)], 1u);
;             asm volatile("s_waitcnt vmcnt(0)" ::: "memory");
;         } else {
;             XB_SPIN(xb_ld(&bar[XB_XGEN(b.x)]) == gen, bar);
.LBB0_150:
	s_or_b64 exec, exec, s[2:3]
	v_cvt_f32_u32_e32 v4, v2
	s_waitcnt vmcnt(0)
	v_readfirstlane_b32 s2, v3
	v_sub_u32_e32 v3, 0, v2
	v_rcp_iflag_f32_e32 v4, v4
	v_add_u32_e32 v5, s2, v1
	v_mul_f32_e32 v4, 0x4f7ffffe, v4
	v_cvt_u32_f32_e32 v4, v4
	v_mul_lo_u32 v1, v3, v4
	v_mul_hi_u32 v1, v4, v1
	v_add_u32_e32 v1, v4, v1
	v_mul_hi_u32 v1, v5, v1
	v_mul_lo_u32 v3, v1, v2
	v_sub_u32_e32 v3, v5, v3
	v_add_u32_e32 v4, 1, v1
	v_cmp_ge_u32_e32 vcc, v3, v2
	s_nop 1
	v_cndmask_b32_e32 v1, v1, v4, vcc
	v_sub_u32_e32 v4, v3, v2
	v_cndmask_b32_e32 v3, v3, v4, vcc
	v_add_u32_e32 v4, 1, v1
	v_cmp_ge_u32_e32 vcc, v3, v2
	v_add_u32_e32 v3, 1, v5
	s_nop 0
	v_cndmask_b32_e32 v1, v1, v4, vcc
	v_mul_lo_u32 v4, v2, v1
	v_add_u32_e32 v2, v4, v2
	v_cmp_ne_u32_e32 vcc, v3, v2
	s_and_saveexec_b64 s[2:3], vcc
	s_xor_b64 s[2:3], exec, s[2:3]
	s_cbranch_execz .LBB0_164
	v_readlane_b32 s4, v251, 11
	s_waitcnt lgkmcnt(0)
	v_mov_b32_e32 v0, 0
	v_readlane_b32 s5, v251, 12
	s_nop 4
	buffer_inv sc1
	global_load_dword v2, v0, s[4:5] sc1
	s_waitcnt vmcnt(0)
	v_cmp_eq_u32_e32 vcc, v2, v1
	s_and_saveexec_b64 s[4:5], vcc
	s_cbranch_execz .LBB0_163
	s_mov_b32 s16, 1
	s_mov_b64 s[6:7], 0
	s_branch .LBB0_154

; __device__ __forceinline__ unsigned xb_ld(unsigned* p)              { return __hip_atomic_load(p, __ATOMIC_RELAXED, __HIP_MEMORY_SCOPE_AGENT); }
; #define XB_SPIN(cond, bar) do { unsigned _sp = 0; while (cond) { __builtin_amdgcn_s_sleep(1); \
;     if ((++_sp & 255u) == 0u) { if (xb_ld(&(bar)[XB_TMO])) break; if (_sp > XB_SPIN_CAP) { atomicAdd(&(bar)[XB_TMO], 1u); break; } } } } while (0)
; __device__ __forceinline__ void xcd_barrier(const XcdBarrier& b) {
;     ...
;             XB_SPIN(xb_ld(&bar[XB_XGEN(b.x)]) == gen, bar);
.LBB0_158:
	v_readlane_b32 s10, v251, 11
	v_readlane_b32 s11, v251, 12
	s_add_i32 s16, s16, 1
	s_mov_b64 s[12:13], -1
	s_nop 2
	global_load_dword v2, v0, s[10:11] sc1
	s_waitcnt vmcnt(0)
	v_cmp_ne_u32_e32 vcc, v2, v1
	s_orn2_b64 s[10:11], vcc, exec
	s_branch .LBB0_153

; __device__ __forceinline__ unsigned xb_ld(unsigned* p)              { return __hip_atomic_load(p, __ATOMIC_RELAXED, __HIP_MEMORY_SCOPE_AGENT); }
; __device__ __forceinline__ unsigned xb_add(unsigned* p, unsigned v) { return __hip_atomic_fetch_add(p, v, __ATOMIC_RELAXED, __HIP_MEMORY_SCOPE_AGENT); }
; #define XB_SPIN(cond, bar) do { unsigned _sp = 0; while (cond) { __builtin_amdgcn_s_sleep(1); \
;     if ((++_sp & 255u) == 0u) { if (xb_ld(&(bar)[XB_TMO])) break; if (_sp > XB_SPIN_CAP) { atomicAdd(&(bar)[XB_TMO], 1u); break; } } } } while (0)
; __device__ __forceinline__ void xcd_barrier(const XcdBarrier& b) {
;     ...
;         unsigned nloc = b.st[0], nx = b.st[1];
;         if (nloc == 0u) { xcd_barrier_complete(bar, b.x, nloc, nx); b.st[0] = nloc; b.st[1] = nx; }
;         const unsigned old = xb_add(&bar[XB_XSUB(b.x)], 1u);
;         const unsigned gen = old / nloc;
;         if (old + 1u == (gen + 1u) * nloc) {
;             __builtin_amdgcn_fence(__ATOMIC_RELEASE, "agent");
;             asm volatile("s_waitcnt vmcnt(0)" ::: "memory");
;             const unsigned og = xb_add(&bar[XB_TOP], 1u);
;             const unsigned tg = og / nx;
;             if (og + 1u == (tg + 1u) * nx) xb_add(&bar[XB_TOPGEN], 1u);
;             else XB_SPIN(xb_ld(&bar[XB_TOPGEN]) == tg, bar);
;             __builtin_amdgcn_fence(__ATOMIC_ACQUIRE, "agent");
;             xb_add(&bar[XB_XGEN(b.x)], 1u);
;             asm volatile("s_waitcnt vmcnt(0)" ::: "memory");
;         } else {
;             XB_SPIN(xb_ld(&bar[XB_XGEN(b.x)]) == gen, bar);
.LBB0_280:
	s_or_b64 exec, exec, s[2:3]
	v_cvt_f32_u32_e32 v5, v3
	s_waitcnt vmcnt(0)
	v_readfirstlane_b32 s2, v4
	v_sub_u32_e32 v4, 0, v3
	v_rcp_iflag_f32_e32 v5, v5
	v_add_u32_e32 v6, s2, v0
	v_mul_f32_e32 v5, 0x4f7ffffe, v5
	v_cvt_u32_f32_e32 v5, v5
	v_mul_lo_u32 v0, v4, v5
	v_mul_hi_u32 v0, v5, v0
	v_add_u32_e32 v0, v5, v0
	v_mul_hi_u32 v0, v6, v0
	v_mul_lo_u32 v4, v0, v3
	v_sub_u32_e32 v4, v6, v4
	v_add_u32_e32 v5, 1, v0
	v_cmp_ge_u32_e32 vcc, v4, v3
	s_nop 1
	v_cndmask_b32_e32 v0, v0, v5, vcc
	v_sub_u32_e32 v5, v4, v3
	v_cndmask_b32_e32 v4, v4, v5, vcc
	v_add_u32_e32 v5, 1, v0
	v_cmp_ge_u32_e32 vcc, v4, v3
	v_add_u32_e32 v4, 1, v6
	s_nop 0
	v_cndmask_b32_e32 v0, v0, v5, vcc
	v_mul_lo_u32 v5, v3, v0
	v_add_u32_e32 v3, v5, v3
	v_cmp_ne_u32_e32 vcc, v4, v3
	s_and_saveexec_b64 s[2:3], vcc
	s_xor_b64 s[2:3], exec, s[2:3]
	s_cbranch_execz .LBB0_294
	v_readlane_b32 s4, v251, 11
	v_readlane_b32 s5, v251, 12
	s_waitcnt lgkmcnt(0)
	s_nop 3
	buffer_inv sc1
	global_load_dword v2, v1, s[4:5] sc1
	s_waitcnt vmcnt(0)
	v_cmp_eq_u32_e32 vcc, v2, v0
	s_and_saveexec_b64 s[4:5], vcc
	s_cbranch_execz .LBB0_293
	s_mov_b32 s16, 1
	s_mov_b64 s[6:7], 0
	s_branch .LBB0_284
